# non-temporal hints on once-touched streams (f32 weights in P0, final-norm row loads and output stores, conv cb loads)
# speedup vs baseline: 1.0052x; 1.0030x over previous
; __device__ __forceinline__ float bf_lo(unsigned u) { return __uint_as_float(u << 16); }
; __device__ __forceinline__ float bf_hi(unsigned u) { return __uint_as_float(u & 0xffff0000u); }
; __global__ void __launch_bounds__(512, 2) fwd_kernel(const Args a) {
;     ...
;             for (int m = gw; m < ML; m += NGW) {
;                 const u32x2* xq = (const u32x2*)(XBb + (size_t)m * D); f32x4* xr = (f32x4*)(out + (size_t)m * D) + lane; f32x4 v[8]; float ss = 0.f;
; #pragma unroll
;                 for (int j = 0; j < 8; ++j) { const u32x2 q = xq[64 * j + lane]; v[j] = (f32x4){bf_lo(q.x), bf_hi(q.x), bf_lo(q.y), bf_hi(q.y)}; ss += (v[j].x * v[j].x + v[j].y * v[j].y) + (v[j].z * v[j].z + v[j].w * v[j].w); }
.LBB0_16:
	s_cmp_eq_u32 s92, 17
	s_mov_b64 s[8:9], -1
	s_cbranch_scc0 .LBB0_21
	v_readlane_b32 s8, v252, 12
	v_readlane_b32 s9, v252, 13
	s_andn2_b64 vcc, exec, s[8:9]
	s_cbranch_vccnz .LBB0_20
	v_readlane_b32 s8, v252, 0
	v_readlane_b32 s9, v252, 1
	v_readlane_b32 s8, v254, 41
	v_lshlrev_b32_e32 v10, 3, v188
	v_mov_b32_e32 v11, v177
	v_readlane_b32 s9, v254, 42
	v_lshlrev_b32_e32 v176, 4, v188
	v_lshlrev_b32_e32 v0, 2, v188
	v_lshl_add_u64 v[10:11], s[8:9], 0, v[10:11]
	v_readlane_b32 s8, v254, 43
	v_readlane_b32 s9, v254, 44
	v_readlane_b32 s10, v252, 2
	v_readlane_b32 s11, v252, 3
	v_or_b32_e32 v2, 0x1000, v176
	v_mov_b32_e32 v3, v177
	v_or_b32_e32 v4, 0x1400, v176
	v_mov_b32_e32 v5, v177
	v_or_b32_e32 v6, 0x1800, v176
	v_mov_b32_e32 v7, v177
	v_or_b32_e32 v8, 0x1c00, v176
	v_mov_b32_e32 v9, v177
	v_lshl_add_u64 v[12:13], s[8:9], 0, v[176:177]
	v_readlane_b32 s8, v255, 19
	v_xor_b32_e32 v14, 4, v0
	v_xor_b32_e32 v15, 8, v0
	v_xor_b32_e32 v16, 16, v0
	v_xor_b32_e32 v17, 32, v0
	v_xor_b32_e32 v18, 64, v0
	v_xor_b32_e32 v19, 0x80, v0
	v_lshl_add_u64 v[0:1], s[10:11], 0, v[176:177]
	v_lshl_add_u64 v[2:3], s[10:11], 0, v[2:3]
	v_lshl_add_u64 v[4:5], s[10:11], 0, v[4:5]
	v_lshl_add_u64 v[6:7], s[10:11], 0, v[6:7]
	v_lshl_add_u64 v[8:9], s[10:11], 0, v[8:9]
	s_mov_b32 s2, s8
	v_readlane_b32 s12, v252, 4
	v_readlane_b32 s13, v252, 5
	v_readlane_b32 s14, v252, 6
	v_readlane_b32 s15, v252, 7
	v_readlane_b32 s9, v255, 20
	global_load_dwordx4 v[96:99], v[0:1], off
	global_load_dwordx4 v[100:103], v[0:1], off offset:1024
	global_load_dwordx4 v[104:107], v[0:1], off offset:2048
	global_load_dwordx4 v[108:111], v[0:1], off offset:3072
	global_load_dwordx4 v[112:115], v[2:3], off
	global_load_dwordx4 v[116:119], v[4:5], off
	global_load_dwordx4 v[120:123], v[6:7], off
	global_load_dwordx4 v[124:127], v[8:9], off
	global_load_dwordx2 v[24:25], v[10:11], off nt
	global_load_dwordx2 v[26:27], v[10:11], off offset:512 nt
	global_load_dwordx2 v[28:29], v[10:11], off offset:1024 nt
	global_load_dwordx2 v[30:31], v[10:11], off offset:1536 nt
	global_load_dwordx2 v[32:33], v[10:11], off offset:2048 nt
	global_load_dwordx2 v[34:35], v[10:11], off offset:2560 nt
	global_load_dwordx2 v[36:37], v[10:11], off offset:3072 nt
	global_load_dwordx2 v[38:39], v[10:11], off offset:3584 nt
	v_lshl_add_u64 v[10:11], v[10:11], 0, s[90:91]
	s_add_i32 s2, s2, s48
	s_waitcnt vmcnt(0)
.Lfn_loop:
	v_lshlrev_b32_e32 v44, 16, v24
	v_and_b32_e32 v45, 0xffff0000, v24
	v_lshlrev_b32_e32 v46, 16, v25
	v_and_b32_e32 v47, 0xffff0000, v25
	v_lshlrev_b32_e32 v48, 16, v26
	v_and_b32_e32 v49, 0xffff0000, v26
	v_lshlrev_b32_e32 v50, 16, v27
	v_and_b32_e32 v51, 0xffff0000, v27
	v_lshlrev_b32_e32 v52, 16, v28
	v_and_b32_e32 v53, 0xffff0000, v28
	v_lshlrev_b32_e32 v54, 16, v29
	v_and_b32_e32 v55, 0xffff0000, v29
	v_lshlrev_b32_e32 v56, 16, v30
	v_and_b32_e32 v57, 0xffff0000, v30
	v_lshlrev_b32_e32 v58, 16, v31
	v_and_b32_e32 v59, 0xffff0000, v31
	v_lshlrev_b32_e32 v60, 16, v32
	v_and_b32_e32 v61, 0xffff0000, v32
	v_lshlrev_b32_e32 v62, 16, v33
	v_and_b32_e32 v63, 0xffff0000, v33
	v_lshlrev_b32_e32 v64, 16, v34
	v_and_b32_e32 v65, 0xffff0000, v34
	v_lshlrev_b32_e32 v66, 16, v35
	v_and_b32_e32 v67, 0xffff0000, v35
	v_lshlrev_b32_e32 v68, 16, v36
	v_and_b32_e32 v69, 0xffff0000, v36
	v_lshlrev_b32_e32 v70, 16, v37
	v_and_b32_e32 v71, 0xffff0000, v37
	v_lshlrev_b32_e32 v72, 16, v38
	v_and_b32_e32 v73, 0xffff0000, v38
	v_lshlrev_b32_e32 v74, 16, v39
	v_and_b32_e32 v75, 0xffff0000, v39
	s_cmpk_gt_i32 s2, 0x3fff
	s_cbranch_scc1 .Lfn_nopf
	global_load_dwordx2 v[24:25], v[10:11], off nt
	global_load_dwordx2 v[26:27], v[10:11], off offset:512 nt
	global_load_dwordx2 v[28:29], v[10:11], off offset:1024 nt
	global_load_dwordx2 v[30:31], v[10:11], off offset:1536 nt
	global_load_dwordx2 v[32:33], v[10:11], off offset:2048 nt
	global_load_dwordx2 v[34:35], v[10:11], off offset:2560 nt
	global_load_dwordx2 v[36:37], v[10:11], off offset:3072 nt
	global_load_dwordx2 v[38:39], v[10:11], off offset:3584 nt
	v_lshl_add_u64 v[10:11], v[10:11], 0, s[90:91]
; __device__ __forceinline__ float bf_lo(unsigned u) { return __uint_as_float(u << 16); }
; __device__ __forceinline__ float bf_hi(unsigned u) { return __uint_as_float(u & 0xffff0000u); }
; __global__ void __launch_bounds__(512, 2) fwd_kernel(const Args a) {
;     ...
;                 for (int j = 0; j < 8; ++j) { const u32x2 q = xq[64 * j + lane]; v[j] = (f32x4){bf_lo(q.x), bf_hi(q.x), bf_lo(q.y), bf_hi(q.y)}; ss += (v[j].x * v[j].x + v[j].y * v[j].y) + (v[j].z * v[j].z + v[j].w * v[j].w); }
;                 const float rs = rsqrtf(wave_sum(ss, lane) * (1.0f / D) + EPS);
; #pragma unroll
;                 for (int j = 0; j < 8; ++j) { const f32x4 g = ((const f32x4*)final_g)[64 * j + lane]; xr[64 * j] = v[j] * rs * g; }
.Lfn_nopf:
	v_pk_mul_f32 v[76:77], v[44:45], v[44:45]
	v_pk_mul_f32 v[78:79], v[46:47], v[46:47]
	v_pk_fma_f32 v[76:77], v[48:49], v[48:49], v[76:77]
	v_pk_fma_f32 v[78:79], v[50:51], v[50:51], v[78:79]
	v_pk_fma_f32 v[76:77], v[52:53], v[52:53], v[76:77]
	v_pk_fma_f32 v[78:79], v[54:55], v[54:55], v[78:79]
	v_pk_fma_f32 v[76:77], v[56:57], v[56:57], v[76:77]
	v_pk_fma_f32 v[78:79], v[58:59], v[58:59], v[78:79]
	v_pk_fma_f32 v[76:77], v[60:61], v[60:61], v[76:77]
	v_pk_fma_f32 v[78:79], v[62:63], v[62:63], v[78:79]
	v_pk_fma_f32 v[76:77], v[64:65], v[64:65], v[76:77]
	v_pk_fma_f32 v[78:79], v[66:67], v[66:67], v[78:79]
	v_pk_fma_f32 v[76:77], v[68:69], v[68:69], v[76:77]
	v_pk_fma_f32 v[78:79], v[70:71], v[70:71], v[78:79]
	v_pk_fma_f32 v[76:77], v[72:73], v[72:73], v[76:77]
	v_pk_fma_f32 v[78:79], v[74:75], v[74:75], v[78:79]
	v_pk_add_f32 v[76:77], v[76:77], v[78:79]
	s_nop 0
	v_add_f32_e32 v80, v76, v77
	ds_bpermute_b32 v81, v14, v80
	s_waitcnt lgkmcnt(0)
	v_add_f32_e32 v80, v80, v81
	ds_bpermute_b32 v81, v15, v80
	s_waitcnt lgkmcnt(0)
	v_add_f32_e32 v80, v80, v81
	ds_bpermute_b32 v81, v16, v80
	s_waitcnt lgkmcnt(0)
	v_add_f32_e32 v80, v80, v81
	ds_bpermute_b32 v81, v17, v80
	s_waitcnt lgkmcnt(0)
	v_add_f32_e32 v80, v80, v81
	ds_bpermute_b32 v81, v18, v80
	s_waitcnt lgkmcnt(0)
	v_add_f32_e32 v80, v80, v81
	ds_bpermute_b32 v81, v19, v80
	s_waitcnt lgkmcnt(0)
	v_add_f32_e32 v80, v80, v81
	v_fmamk_f32 v80, v80, 0x3a000000, v216
	v_mul_f32_e32 v81, 0x4b800000, v80
	v_cmp_gt_f32_e32 vcc, s44, v80
	v_add_co_u32_e64 v40, s[8:9], s95, v12
	s_nop 1
	v_cndmask_b32_e32 v80, v80, v81, vcc
	v_rsq_f32_e32 v80, v80
	v_addc_co_u32_e64 v41, s[8:9], -1, v13, s[8:9]
	s_nop 0
	v_mul_f32_e32 v81, 0x45800000, v80
	v_cndmask_b32_e32 v80, v80, v81, vcc
	v_pk_mul_f32 v[128:129], v[80:81], v[44:45] op_sel_hi:[0,1]
	v_pk_mul_f32 v[130:131], v[80:81], v[46:47] op_sel_hi:[0,1]
	v_pk_mul_f32 v[128:129], v[96:97], v[128:129]
	v_pk_mul_f32 v[130:131], v[98:99], v[130:131]
	global_store_dwordx4 v[40:41], v[128:131], off offset:-3072 nt
	v_pk_mul_f32 v[132:133], v[80:81], v[48:49] op_sel_hi:[0,1]
	v_pk_mul_f32 v[134:135], v[80:81], v[50:51] op_sel_hi:[0,1]
	v_pk_mul_f32 v[132:133], v[100:101], v[132:133]
	v_pk_mul_f32 v[134:135], v[102:103], v[134:135]
	global_store_dwordx4 v[40:41], v[132:135], off offset:-2048 nt
	v_pk_mul_f32 v[136:137], v[80:81], v[52:53] op_sel_hi:[0,1]
	v_pk_mul_f32 v[138:139], v[80:81], v[54:55] op_sel_hi:[0,1]
	v_pk_mul_f32 v[136:137], v[104:105], v[136:137]
	v_pk_mul_f32 v[138:139], v[106:107], v[138:139]
	global_store_dwordx4 v[40:41], v[136:139], off offset:-1024 nt
	v_pk_mul_f32 v[140:141], v[80:81], v[56:57] op_sel_hi:[0,1]
	v_pk_mul_f32 v[142:143], v[80:81], v[58:59] op_sel_hi:[0,1]
	v_pk_mul_f32 v[140:141], v[108:109], v[140:141]
	v_pk_mul_f32 v[142:143], v[110:111], v[142:143]
	global_store_dwordx4 v[12:13], v[140:143], off offset:-4096 nt
	v_pk_mul_f32 v[144:145], v[80:81], v[60:61] op_sel_hi:[0,1]
	v_pk_mul_f32 v[146:147], v[80:81], v[62:63] op_sel_hi:[0,1]
	v_pk_mul_f32 v[144:145], v[112:113], v[144:145]
	v_pk_mul_f32 v[146:147], v[114:115], v[146:147]
	global_store_dwordx4 v[12:13], v[144:147], off offset:-3072 nt
	v_pk_mul_f32 v[148:149], v[80:81], v[64:65] op_sel_hi:[0,1]
	v_pk_mul_f32 v[150:151], v[80:81], v[66:67] op_sel_hi:[0,1]
	v_pk_mul_f32 v[148:149], v[116:117], v[148:149]
	v_pk_mul_f32 v[150:151], v[118:119], v[150:151]
	global_store_dwordx4 v[12:13], v[148:151], off offset:-2048 nt
	v_pk_mul_f32 v[152:153], v[80:81], v[68:69] op_sel_hi:[0,1]
	v_pk_mul_f32 v[154:155], v[80:81], v[70:71] op_sel_hi:[0,1]
	v_pk_mul_f32 v[152:153], v[120:121], v[152:153]
	v_pk_mul_f32 v[154:155], v[122:123], v[154:155]
	global_store_dwordx4 v[12:13], v[152:155], off offset:-1024 nt
	v_pk_mul_f32 v[156:157], v[80:81], v[72:73] op_sel_hi:[0,1]
	v_pk_mul_f32 v[158:159], v[80:81], v[74:75] op_sel_hi:[0,1]
	v_pk_mul_f32 v[156:157], v[124:125], v[156:157]
	v_pk_mul_f32 v[158:159], v[126:127], v[158:159]
	global_store_dwordx4 v[12:13], v[156:159], off nt
	v_lshl_add_u64 v[12:13], v[12:13], 0, s[40:41]
	s_cmpk_gt_i32 s2, 0x3fff
	s_cbranch_scc1 .LBB0_20
	s_add_i32 s2, s2, s48
	s_waitcnt vmcnt(8)
	s_branch .Lfn_loop

; __global__ void __launch_bounds__(512, 2) fwd_kernel(const Args a) {
;     ...
;                 for (int m = gw; m < mend; m += NGW) {
;                     const bool lat = m < ML; const int t = lat ? (m & (SEQ - 1)) : ((m - ML) & (CTXL - 1)); const int tl = lat ? SEQ - 1 : CTXL - 1;
;                     const bool hp = t > 0, hn = t < tl;
; #pragma unroll
;                     for (int j = 0; j < 4; ++j) {
;                         const int c0 = (64 * j + lane) * 8; const size_t o = (size_t)m * D + c0;
;                         const u32x4 zz = (u32x4){0u, 0u, 0u, 0u};
;                         const u32x4 up = hp ? *(const u32x4*)(Ub + o - D) : zz, uc = *(const u32x4*)(Ub + o), un = hn ? *(const u32x4*)(Ub + o + D) : zz, cb = *(const u32x4*)(CBb + o);
;                         const f32x4 w0a = *(const f32x4*)(cw + c0), w0b = *(const f32x4*)(cw + c0 + 4), w1a = *(const f32x4*)(cw + D + c0), w1b = *(const f32x4*)(cw + D + c0 + 4);
;                         const f32x4 w2a = *(const f32x4*)(cw + 2 * D + c0), w2b = *(const f32x4*)(cw + 2 * D + c0 + 4), ba = *(const f32x4*)(cbias + c0), bb = *(const f32x4*)(cbias + c0 + 4);
.Lcv_allwg:
	s_and_b32 s1, s13, 3
	s_lshr_b32 s4, s13, 2
	s_lshl_b32 s14, s1, 11
	s_mov_b32 s15, 0
	v_lshl_add_u64 v[16:17], v[16:17], 0, s[14:15]
	v_lshl_add_u64 v[18:19], v[18:19], 0, s[14:15]
	v_lshl_add_u64 v[20:21], v[20:21], 0, s[14:15]
	v_lshl_add_u64 v[22:23], v[22:23], 0, s[14:15]
	global_load_dwordx4 v[128:131], v[16:17], off
	global_load_dwordx4 v[132:135], v[16:17], off offset:16
	global_load_dwordx4 v[136:139], v[18:19], off
	global_load_dwordx4 v[140:143], v[18:19], off offset:16
	global_load_dwordx4 v[144:147], v[20:21], off
	global_load_dwordx4 v[148:151], v[20:21], off offset:16
	global_load_dwordx4 v[152:155], v[22:23], off
	global_load_dwordx4 v[156:159], v[22:23], off offset:16
	v_readlane_b32 s8, v254, 49
	v_readlane_b32 s9, v254, 50
	s_lshl_b32 s10, s0, 12
	s_sub_u32 s8, s8, s10
	s_subb_u32 s9, s9, 0
	s_sub_u32 s8, s8, 0x1c00
	s_subb_u32 s9, s9, 0
	s_lshl_b32 s10, s4, 12
	s_lshl_b32 s11, s1, 10
	s_add_u32 s10, s10, s11
	s_add_u32 s8, s8, s10
	s_addc_u32 s9, s9, 0
	v_lshlrev_b32_e32 v0, 4, v188
	v_mov_b32_e32 v1, 0
	v_lshl_add_u64 v[160:161], s[8:9], 0, v[0:1]
	s_sub_u32 s10, s8, 0x4200000
	s_subb_u32 s11, s9, 0
	v_lshl_add_u64 v[164:165], s[10:11], 0, v[0:1]
	v_mov_b32_e32 v166, v164
	v_mov_b32_e32 v167, v165
	s_mov_b64 s[14:15], 0x1000
	v_lshl_add_u64 v[162:163], v[160:161], 0, s[14:15]
	s_lshl_b32 s14, s12, 12
	s_mov_b32 s15, 0
	global_load_dwordx4 v[64:67], v[160:161], off offset:-4096
	global_load_dwordx4 v[68:71], v[160:161], off
	global_load_dwordx4 v[72:75], v[162:163], off
	global_load_dwordx4 v[76:79], v[164:165], off nt
	v_lshl_add_u64 v[160:161], v[160:161], 0, s[14:15]
	v_lshl_add_u64 v[162:163], v[162:163], 0, s[14:15]
	v_lshl_add_u64 v[164:165], v[164:165], 0, s[14:15]
	global_load_dwordx4 v[80:83], v[160:161], off offset:-4096
	global_load_dwordx4 v[84:87], v[160:161], off
	global_load_dwordx4 v[88:91], v[162:163], off
	global_load_dwordx4 v[92:95], v[164:165], off nt
	v_lshl_add_u64 v[160:161], v[160:161], 0, s[14:15]
	v_lshl_add_u64 v[162:163], v[162:163], 0, s[14:15]
	v_lshl_add_u64 v[164:165], v[164:165], 0, s[14:15]
	global_load_dwordx4 v[96:99], v[160:161], off offset:-4096
	global_load_dwordx4 v[100:103], v[160:161], off
	global_load_dwordx4 v[104:107], v[162:163], off
	global_load_dwordx4 v[108:111], v[164:165], off nt
	v_lshl_add_u64 v[160:161], v[160:161], 0, s[14:15]
	v_lshl_add_u64 v[162:163], v[162:163], 0, s[14:15]
	v_lshl_add_u64 v[164:165], v[164:165], 0, s[14:15]
	global_load_dwordx4 v[112:115], v[160:161], off offset:-4096
	global_load_dwordx4 v[116:119], v[160:161], off
	global_load_dwordx4 v[120:123], v[162:163], off
	global_load_dwordx4 v[124:127], v[164:165], off nt
	v_lshl_add_u64 v[160:161], v[160:161], 0, s[14:15]
	v_lshl_add_u64 v[162:163], v[162:163], 0, s[14:15]
	v_lshl_add_u64 v[164:165], v[164:165], 0, s[14:15]

; __device__ __forceinline__ u32x4 pack8(const f32x4 a, const f32x4 b) { u32x4 w; w.x = cvt_pk_bf16(a[0], a[1]); w.y = cvt_pk_bf16(a[2], a[3]); w.z = cvt_pk_bf16(b[0], b[1]); w.w = cvt_pk_bf16(b[2], b[3]); return w; }
; #define UNPK_LO(q) ((f32x4){bf_lo(q.x), bf_hi(q.x), bf_lo(q.y), bf_hi(q.y)})
; #define UNPK_HI(q) ((f32x4){bf_lo(q.z), bf_hi(q.z), bf_lo(q.w), bf_hi(q.w)})
; __global__ void __launch_bounds__(512, 2) fwd_kernel(const Args a) {
;     ...
;                         const int c0 = (64 * j + lane) * 8; const size_t o = (size_t)m * D + c0;
;                         const u32x4 zz = (u32x4){0u, 0u, 0u, 0u};
;                         const u32x4 up = hp ? *(const u32x4*)(Ub + o - D) : zz, uc = *(const u32x4*)(Ub + o), un = hn ? *(const u32x4*)(Ub + o + D) : zz, cb = *(const u32x4*)(CBb + o);
;                         const f32x4 w0a = *(const f32x4*)(cw + c0), w0b = *(const f32x4*)(cw + c0 + 4), w1a = *(const f32x4*)(cw + D + c0), w1b = *(const f32x4*)(cw + D + c0 + 4);
;                         const f32x4 w2a = *(const f32x4*)(cw + 2 * D + c0), w2b = *(const f32x4*)(cw + 2 * D + c0 + 4), ba = *(const f32x4*)(cbias + c0), bb = *(const f32x4*)(cbias + c0 + 4);
;     ...
;                         const f32x4 ya = UNPK_LO(cb) * (w0a * UNPK_LO(up) + w1a * UNPK_LO(uc) + w2a * UNPK_LO(un) + ba);
;                         const f32x4 yb = UNPK_HI(cb) * (w0b * UNPK_HI(up) + w1b * UNPK_HI(uc) + w2b * UNPK_HI(un) + bb);
;     ...
;                         *(u32x4*)(CBb + o) = pack8(ya, yb);
.Lcv_hn0:
	v_lshlrev_b32_e32 v0, 16, v64
	v_and_b32_e32 v1, 0xffff0000, v64
	v_lshlrev_b32_e32 v2, 16, v65
	v_and_b32_e32 v3, 0xffff0000, v65
	v_lshlrev_b32_e32 v4, 16, v66
	v_and_b32_e32 v5, 0xffff0000, v66
	v_lshlrev_b32_e32 v6, 16, v67
	v_and_b32_e32 v7, 0xffff0000, v67
	v_lshlrev_b32_e32 v8, 16, v68
	v_and_b32_e32 v9, 0xffff0000, v68
	v_lshlrev_b32_e32 v10, 16, v69
	v_and_b32_e32 v11, 0xffff0000, v69
	v_lshlrev_b32_e32 v12, 16, v70
	v_and_b32_e32 v13, 0xffff0000, v70
	v_lshlrev_b32_e32 v14, 16, v71
	v_and_b32_e32 v15, 0xffff0000, v71
	v_lshlrev_b32_e32 v16, 16, v72
	v_and_b32_e32 v17, 0xffff0000, v72
	v_lshlrev_b32_e32 v18, 16, v73
	v_and_b32_e32 v19, 0xffff0000, v73
	v_lshlrev_b32_e32 v20, 16, v74
	v_and_b32_e32 v21, 0xffff0000, v74
	v_lshlrev_b32_e32 v22, 16, v75
	v_and_b32_e32 v23, 0xffff0000, v75
	v_lshlrev_b32_e32 v24, 16, v76
	v_and_b32_e32 v25, 0xffff0000, v76
	v_lshlrev_b32_e32 v26, 16, v77
	v_and_b32_e32 v27, 0xffff0000, v77
	v_lshlrev_b32_e32 v28, 16, v78
	v_and_b32_e32 v29, 0xffff0000, v78
	v_lshlrev_b32_e32 v30, 16, v79
	v_and_b32_e32 v31, 0xffff0000, v79
	global_load_dwordx4 v[64:67], v[160:161], off offset:-4096
	global_load_dwordx4 v[68:71], v[160:161], off
	global_load_dwordx4 v[72:75], v[162:163], off
	global_load_dwordx4 v[76:79], v[164:165], off nt
	v_lshl_add_u64 v[160:161], v[160:161], 0, s[14:15]
	v_lshl_add_u64 v[162:163], v[162:163], 0, s[14:15]
	v_lshl_add_u64 v[164:165], v[164:165], 0, s[14:15]
	v_pk_mul_f32 v[48:49], v[136:137], v[8:9]
	v_pk_fma_f32 v[48:49], v[128:129], v[0:1], v[48:49]
	v_pk_fma_f32 v[48:49], v[144:145], v[16:17], v[48:49]
	v_pk_add_f32 v[48:49], v[152:153], v[48:49]
	v_pk_mul_f32 v[56:57], v[48:49], v[24:25]
	v_pk_mul_f32 v[50:51], v[138:139], v[10:11]
	v_pk_fma_f32 v[50:51], v[130:131], v[2:3], v[50:51]
	v_pk_fma_f32 v[50:51], v[146:147], v[18:19], v[50:51]
	v_pk_add_f32 v[50:51], v[154:155], v[50:51]
	v_pk_mul_f32 v[58:59], v[50:51], v[26:27]
	v_pk_mul_f32 v[52:53], v[140:141], v[12:13]
	v_pk_fma_f32 v[52:53], v[132:133], v[4:5], v[52:53]
	v_pk_fma_f32 v[52:53], v[148:149], v[20:21], v[52:53]
	v_pk_add_f32 v[52:53], v[156:157], v[52:53]
	v_pk_mul_f32 v[60:61], v[52:53], v[28:29]
	v_pk_mul_f32 v[54:55], v[142:143], v[14:15]
	v_pk_fma_f32 v[54:55], v[134:135], v[6:7], v[54:55]
	v_pk_fma_f32 v[54:55], v[150:151], v[22:23], v[54:55]
	v_pk_add_f32 v[54:55], v[158:159], v[54:55]
	v_pk_mul_f32 v[62:63], v[54:55], v[30:31]
	v_cvt_pk_bf16_f32 v32, v56, v57
	v_cvt_pk_bf16_f32 v33, v58, v59
	v_cvt_pk_bf16_f32 v34, v60, v61
	v_cvt_pk_bf16_f32 v35, v62, v63
	global_store_dwordx4 v[166:167], v[32:35], off
	v_lshl_add_u64 v[166:167], v[166:167], 0, s[14:15]
	s_add_u32 s4, s4, s12
	s_cmp_ge_u32 s4, s2
	s_cbranch_scc1 .Lcv_done
	s_movk_i32 s9, 0xff
	s_cmpk_lt_u32 s4, 0x4000
	s_cselect_b32 s8, 0x1fff, s9
	s_and_b32 s9, s4, s8
	s_waitcnt vmcnt(12)
	s_cmp_lg_u32 s9, 0
	s_cbranch_scc1 .Lcv_hp1
	v_mov_b32_e32 v80, 0
	v_mov_b32_e32 v81, 0
	v_mov_b32_e32 v82, 0
	v_mov_b32_e32 v83, 0

; __device__ __forceinline__ u32x4 pack8(const f32x4 a, const f32x4 b) { u32x4 w; w.x = cvt_pk_bf16(a[0], a[1]); w.y = cvt_pk_bf16(a[2], a[3]); w.z = cvt_pk_bf16(b[0], b[1]); w.w = cvt_pk_bf16(b[2], b[3]); return w; }
; #define UNPK_LO(q) ((f32x4){bf_lo(q.x), bf_hi(q.x), bf_lo(q.y), bf_hi(q.y)})
; #define UNPK_HI(q) ((f32x4){bf_lo(q.z), bf_hi(q.z), bf_lo(q.w), bf_hi(q.w)})
; __global__ void __launch_bounds__(512, 2) fwd_kernel(const Args a) {
;     ...
;                         const int c0 = (64 * j + lane) * 8; const size_t o = (size_t)m * D + c0;
;                         const u32x4 zz = (u32x4){0u, 0u, 0u, 0u};
;                         const u32x4 up = hp ? *(const u32x4*)(Ub + o - D) : zz, uc = *(const u32x4*)(Ub + o), un = hn ? *(const u32x4*)(Ub + o + D) : zz, cb = *(const u32x4*)(CBb + o);
;                         const f32x4 w0a = *(const f32x4*)(cw + c0), w0b = *(const f32x4*)(cw + c0 + 4), w1a = *(const f32x4*)(cw + D + c0), w1b = *(const f32x4*)(cw + D + c0 + 4);
;                         const f32x4 w2a = *(const f32x4*)(cw + 2 * D + c0), w2b = *(const f32x4*)(cw + 2 * D + c0 + 4), ba = *(const f32x4*)(cbias + c0), bb = *(const f32x4*)(cbias + c0 + 4);
;     ...
;                         const f32x4 ya = UNPK_LO(cb) * (w0a * UNPK_LO(up) + w1a * UNPK_LO(uc) + w2a * UNPK_LO(un) + ba);
;                         const f32x4 yb = UNPK_HI(cb) * (w0b * UNPK_HI(up) + w1b * UNPK_HI(uc) + w2b * UNPK_HI(un) + bb);
;     ...
;                         *(u32x4*)(CBb + o) = pack8(ya, yb);
.Lcv_hn1:
	v_lshlrev_b32_e32 v0, 16, v80
	v_and_b32_e32 v1, 0xffff0000, v80
	v_lshlrev_b32_e32 v2, 16, v81
	v_and_b32_e32 v3, 0xffff0000, v81
	v_lshlrev_b32_e32 v4, 16, v82
	v_and_b32_e32 v5, 0xffff0000, v82
	v_lshlrev_b32_e32 v6, 16, v83
	v_and_b32_e32 v7, 0xffff0000, v83
	v_lshlrev_b32_e32 v8, 16, v84
	v_and_b32_e32 v9, 0xffff0000, v84
	v_lshlrev_b32_e32 v10, 16, v85
	v_and_b32_e32 v11, 0xffff0000, v85
	v_lshlrev_b32_e32 v12, 16, v86
	v_and_b32_e32 v13, 0xffff0000, v86
	v_lshlrev_b32_e32 v14, 16, v87
	v_and_b32_e32 v15, 0xffff0000, v87
	v_lshlrev_b32_e32 v16, 16, v88
	v_and_b32_e32 v17, 0xffff0000, v88
	v_lshlrev_b32_e32 v18, 16, v89
	v_and_b32_e32 v19, 0xffff0000, v89
	v_lshlrev_b32_e32 v20, 16, v90
	v_and_b32_e32 v21, 0xffff0000, v90
	v_lshlrev_b32_e32 v22, 16, v91
	v_and_b32_e32 v23, 0xffff0000, v91
	v_lshlrev_b32_e32 v24, 16, v92
	v_and_b32_e32 v25, 0xffff0000, v92
	v_lshlrev_b32_e32 v26, 16, v93
	v_and_b32_e32 v27, 0xffff0000, v93
	v_lshlrev_b32_e32 v28, 16, v94
	v_and_b32_e32 v29, 0xffff0000, v94
	v_lshlrev_b32_e32 v30, 16, v95
	v_and_b32_e32 v31, 0xffff0000, v95
	global_load_dwordx4 v[80:83], v[160:161], off offset:-4096
	global_load_dwordx4 v[84:87], v[160:161], off
	global_load_dwordx4 v[88:91], v[162:163], off
	global_load_dwordx4 v[92:95], v[164:165], off nt
	v_lshl_add_u64 v[160:161], v[160:161], 0, s[14:15]
	v_lshl_add_u64 v[162:163], v[162:163], 0, s[14:15]
	v_lshl_add_u64 v[164:165], v[164:165], 0, s[14:15]
	v_pk_mul_f32 v[48:49], v[136:137], v[8:9]
	v_pk_fma_f32 v[48:49], v[128:129], v[0:1], v[48:49]
	v_pk_fma_f32 v[48:49], v[144:145], v[16:17], v[48:49]
	v_pk_add_f32 v[48:49], v[152:153], v[48:49]
	v_pk_mul_f32 v[56:57], v[48:49], v[24:25]
	v_pk_mul_f32 v[50:51], v[138:139], v[10:11]
	v_pk_fma_f32 v[50:51], v[130:131], v[2:3], v[50:51]
	v_pk_fma_f32 v[50:51], v[146:147], v[18:19], v[50:51]
	v_pk_add_f32 v[50:51], v[154:155], v[50:51]
	v_pk_mul_f32 v[58:59], v[50:51], v[26:27]
	v_pk_mul_f32 v[52:53], v[140:141], v[12:13]
	v_pk_fma_f32 v[52:53], v[132:133], v[4:5], v[52:53]
	v_pk_fma_f32 v[52:53], v[148:149], v[20:21], v[52:53]
	v_pk_add_f32 v[52:53], v[156:157], v[52:53]
	v_pk_mul_f32 v[60:61], v[52:53], v[28:29]
	v_pk_mul_f32 v[54:55], v[142:143], v[14:15]
	v_pk_fma_f32 v[54:55], v[134:135], v[6:7], v[54:55]
	v_pk_fma_f32 v[54:55], v[150:151], v[22:23], v[54:55]
	v_pk_add_f32 v[54:55], v[158:159], v[54:55]
	v_pk_mul_f32 v[62:63], v[54:55], v[30:31]
	v_cvt_pk_bf16_f32 v36, v56, v57
	v_cvt_pk_bf16_f32 v37, v58, v59
	v_cvt_pk_bf16_f32 v38, v60, v61
	v_cvt_pk_bf16_f32 v39, v62, v63
	global_store_dwordx4 v[166:167], v[36:39], off
	v_lshl_add_u64 v[166:167], v[166:167], 0, s[14:15]
	s_add_u32 s4, s4, s12
	s_cmp_ge_u32 s4, s2
	s_cbranch_scc1 .Lcv_done
	s_movk_i32 s9, 0xff
	s_cmpk_lt_u32 s4, 0x4000
	s_cselect_b32 s8, 0x1fff, s9
	s_and_b32 s9, s4, s8
	s_waitcnt vmcnt(12)
	s_cmp_lg_u32 s9, 0
	s_cbranch_scc1 .Lcv_hp2
	v_mov_b32_e32 v96, 0
	v_mov_b32_e32 v97, 0
	v_mov_b32_e32 v98, 0
	v_mov_b32_e32 v99, 0

; __device__ __forceinline__ u32x4 pack8(const f32x4 a, const f32x4 b) { u32x4 w; w.x = cvt_pk_bf16(a[0], a[1]); w.y = cvt_pk_bf16(a[2], a[3]); w.z = cvt_pk_bf16(b[0], b[1]); w.w = cvt_pk_bf16(b[2], b[3]); return w; }
; #define UNPK_LO(q) ((f32x4){bf_lo(q.x), bf_hi(q.x), bf_lo(q.y), bf_hi(q.y)})
; #define UNPK_HI(q) ((f32x4){bf_lo(q.z), bf_hi(q.z), bf_lo(q.w), bf_hi(q.w)})
; __global__ void __launch_bounds__(512, 2) fwd_kernel(const Args a) {
;     ...
;                         const int c0 = (64 * j + lane) * 8; const size_t o = (size_t)m * D + c0;
;                         const u32x4 zz = (u32x4){0u, 0u, 0u, 0u};
;                         const u32x4 up = hp ? *(const u32x4*)(Ub + o - D) : zz, uc = *(const u32x4*)(Ub + o), un = hn ? *(const u32x4*)(Ub + o + D) : zz, cb = *(const u32x4*)(CBb + o);
;                         const f32x4 w0a = *(const f32x4*)(cw + c0), w0b = *(const f32x4*)(cw + c0 + 4), w1a = *(const f32x4*)(cw + D + c0), w1b = *(const f32x4*)(cw + D + c0 + 4);
;                         const f32x4 w2a = *(const f32x4*)(cw + 2 * D + c0), w2b = *(const f32x4*)(cw + 2 * D + c0 + 4), ba = *(const f32x4*)(cbias + c0), bb = *(const f32x4*)(cbias + c0 + 4);
;     ...
;                         const f32x4 ya = UNPK_LO(cb) * (w0a * UNPK_LO(up) + w1a * UNPK_LO(uc) + w2a * UNPK_LO(un) + ba);
;                         const f32x4 yb = UNPK_HI(cb) * (w0b * UNPK_HI(up) + w1b * UNPK_HI(uc) + w2b * UNPK_HI(un) + bb);
;     ...
;                         *(u32x4*)(CBb + o) = pack8(ya, yb);
.Lcv_hn2:
	v_lshlrev_b32_e32 v0, 16, v96
	v_and_b32_e32 v1, 0xffff0000, v96
	v_lshlrev_b32_e32 v2, 16, v97
	v_and_b32_e32 v3, 0xffff0000, v97
	v_lshlrev_b32_e32 v4, 16, v98
	v_and_b32_e32 v5, 0xffff0000, v98
	v_lshlrev_b32_e32 v6, 16, v99
	v_and_b32_e32 v7, 0xffff0000, v99
	v_lshlrev_b32_e32 v8, 16, v100
	v_and_b32_e32 v9, 0xffff0000, v100
	v_lshlrev_b32_e32 v10, 16, v101
	v_and_b32_e32 v11, 0xffff0000, v101
	v_lshlrev_b32_e32 v12, 16, v102
	v_and_b32_e32 v13, 0xffff0000, v102
	v_lshlrev_b32_e32 v14, 16, v103
	v_and_b32_e32 v15, 0xffff0000, v103
	v_lshlrev_b32_e32 v16, 16, v104
	v_and_b32_e32 v17, 0xffff0000, v104
	v_lshlrev_b32_e32 v18, 16, v105
	v_and_b32_e32 v19, 0xffff0000, v105
	v_lshlrev_b32_e32 v20, 16, v106
	v_and_b32_e32 v21, 0xffff0000, v106
	v_lshlrev_b32_e32 v22, 16, v107
	v_and_b32_e32 v23, 0xffff0000, v107
	v_lshlrev_b32_e32 v24, 16, v108
	v_and_b32_e32 v25, 0xffff0000, v108
	v_lshlrev_b32_e32 v26, 16, v109
	v_and_b32_e32 v27, 0xffff0000, v109
	v_lshlrev_b32_e32 v28, 16, v110
	v_and_b32_e32 v29, 0xffff0000, v110
	v_lshlrev_b32_e32 v30, 16, v111
	v_and_b32_e32 v31, 0xffff0000, v111
	global_load_dwordx4 v[96:99], v[160:161], off offset:-4096
	global_load_dwordx4 v[100:103], v[160:161], off
	global_load_dwordx4 v[104:107], v[162:163], off
	global_load_dwordx4 v[108:111], v[164:165], off nt
	v_lshl_add_u64 v[160:161], v[160:161], 0, s[14:15]
	v_lshl_add_u64 v[162:163], v[162:163], 0, s[14:15]
	v_lshl_add_u64 v[164:165], v[164:165], 0, s[14:15]
	v_pk_mul_f32 v[48:49], v[136:137], v[8:9]
	v_pk_fma_f32 v[48:49], v[128:129], v[0:1], v[48:49]
	v_pk_fma_f32 v[48:49], v[144:145], v[16:17], v[48:49]
	v_pk_add_f32 v[48:49], v[152:153], v[48:49]
	v_pk_mul_f32 v[56:57], v[48:49], v[24:25]
	v_pk_mul_f32 v[50:51], v[138:139], v[10:11]
	v_pk_fma_f32 v[50:51], v[130:131], v[2:3], v[50:51]
	v_pk_fma_f32 v[50:51], v[146:147], v[18:19], v[50:51]
	v_pk_add_f32 v[50:51], v[154:155], v[50:51]
	v_pk_mul_f32 v[58:59], v[50:51], v[26:27]
	v_pk_mul_f32 v[52:53], v[140:141], v[12:13]
	v_pk_fma_f32 v[52:53], v[132:133], v[4:5], v[52:53]
	v_pk_fma_f32 v[52:53], v[148:149], v[20:21], v[52:53]
	v_pk_add_f32 v[52:53], v[156:157], v[52:53]
	v_pk_mul_f32 v[60:61], v[52:53], v[28:29]
	v_pk_mul_f32 v[54:55], v[142:143], v[14:15]
	v_pk_fma_f32 v[54:55], v[134:135], v[6:7], v[54:55]
	v_pk_fma_f32 v[54:55], v[150:151], v[22:23], v[54:55]
	v_pk_add_f32 v[54:55], v[158:159], v[54:55]
	v_pk_mul_f32 v[62:63], v[54:55], v[30:31]
	v_cvt_pk_bf16_f32 v40, v56, v57
	v_cvt_pk_bf16_f32 v41, v58, v59
	v_cvt_pk_bf16_f32 v42, v60, v61
	v_cvt_pk_bf16_f32 v43, v62, v63
	global_store_dwordx4 v[166:167], v[40:43], off
	v_lshl_add_u64 v[166:167], v[166:167], 0, s[14:15]
	s_add_u32 s4, s4, s12
	s_cmp_ge_u32 s4, s2
	s_cbranch_scc1 .Lcv_done
	s_movk_i32 s9, 0xff
	s_cmpk_lt_u32 s4, 0x4000
	s_cselect_b32 s8, 0x1fff, s9
	s_and_b32 s9, s4, s8
	s_waitcnt vmcnt(12)
	s_cmp_lg_u32 s9, 0
	s_cbranch_scc1 .Lcv_hp3
	v_mov_b32_e32 v112, 0
	v_mov_b32_e32 v113, 0
	v_mov_b32_e32 v114, 0
	v_mov_b32_e32 v115, 0

; __device__ __forceinline__ u32x4 pack8(const f32x4 a, const f32x4 b) { u32x4 w; w.x = cvt_pk_bf16(a[0], a[1]); w.y = cvt_pk_bf16(a[2], a[3]); w.z = cvt_pk_bf16(b[0], b[1]); w.w = cvt_pk_bf16(b[2], b[3]); return w; }
; #define UNPK_LO(q) ((f32x4){bf_lo(q.x), bf_hi(q.x), bf_lo(q.y), bf_hi(q.y)})
; #define UNPK_HI(q) ((f32x4){bf_lo(q.z), bf_hi(q.z), bf_lo(q.w), bf_hi(q.w)})
; __global__ void __launch_bounds__(512, 2) fwd_kernel(const Args a) {
;     ...
;                         const int c0 = (64 * j + lane) * 8; const size_t o = (size_t)m * D + c0;
;                         const u32x4 zz = (u32x4){0u, 0u, 0u, 0u};
;                         const u32x4 up = hp ? *(const u32x4*)(Ub + o - D) : zz, uc = *(const u32x4*)(Ub + o), un = hn ? *(const u32x4*)(Ub + o + D) : zz, cb = *(const u32x4*)(CBb + o);
;                         const f32x4 w0a = *(const f32x4*)(cw + c0), w0b = *(const f32x4*)(cw + c0 + 4), w1a = *(const f32x4*)(cw + D + c0), w1b = *(const f32x4*)(cw + D + c0 + 4);
;                         const f32x4 w2a = *(const f32x4*)(cw + 2 * D + c0), w2b = *(const f32x4*)(cw + 2 * D + c0 + 4), ba = *(const f32x4*)(cbias + c0), bb = *(const f32x4*)(cbias + c0 + 4);
;     ...
;                         const f32x4 ya = UNPK_LO(cb) * (w0a * UNPK_LO(up) + w1a * UNPK_LO(uc) + w2a * UNPK_LO(un) + ba);
;                         const f32x4 yb = UNPK_HI(cb) * (w0b * UNPK_HI(up) + w1b * UNPK_HI(uc) + w2b * UNPK_HI(un) + bb);
;     ...
;                         *(u32x4*)(CBb + o) = pack8(ya, yb);
.Lcv_hn3:
	v_lshlrev_b32_e32 v0, 16, v112
	v_and_b32_e32 v1, 0xffff0000, v112
	v_lshlrev_b32_e32 v2, 16, v113
	v_and_b32_e32 v3, 0xffff0000, v113
	v_lshlrev_b32_e32 v4, 16, v114
	v_and_b32_e32 v5, 0xffff0000, v114
	v_lshlrev_b32_e32 v6, 16, v115
	v_and_b32_e32 v7, 0xffff0000, v115
	v_lshlrev_b32_e32 v8, 16, v116
	v_and_b32_e32 v9, 0xffff0000, v116
	v_lshlrev_b32_e32 v10, 16, v117
	v_and_b32_e32 v11, 0xffff0000, v117
	v_lshlrev_b32_e32 v12, 16, v118
	v_and_b32_e32 v13, 0xffff0000, v118
	v_lshlrev_b32_e32 v14, 16, v119
	v_and_b32_e32 v15, 0xffff0000, v119
	v_lshlrev_b32_e32 v16, 16, v120
	v_and_b32_e32 v17, 0xffff0000, v120
	v_lshlrev_b32_e32 v18, 16, v121
	v_and_b32_e32 v19, 0xffff0000, v121
	v_lshlrev_b32_e32 v20, 16, v122
	v_and_b32_e32 v21, 0xffff0000, v122
	v_lshlrev_b32_e32 v22, 16, v123
	v_and_b32_e32 v23, 0xffff0000, v123
	v_lshlrev_b32_e32 v24, 16, v124
	v_and_b32_e32 v25, 0xffff0000, v124
	v_lshlrev_b32_e32 v26, 16, v125
	v_and_b32_e32 v27, 0xffff0000, v125
	v_lshlrev_b32_e32 v28, 16, v126
	v_and_b32_e32 v29, 0xffff0000, v126
	v_lshlrev_b32_e32 v30, 16, v127
	v_and_b32_e32 v31, 0xffff0000, v127
	global_load_dwordx4 v[112:115], v[160:161], off offset:-4096
	global_load_dwordx4 v[116:119], v[160:161], off
	global_load_dwordx4 v[120:123], v[162:163], off
	global_load_dwordx4 v[124:127], v[164:165], off nt
	v_lshl_add_u64 v[160:161], v[160:161], 0, s[14:15]
	v_lshl_add_u64 v[162:163], v[162:163], 0, s[14:15]
	v_lshl_add_u64 v[164:165], v[164:165], 0, s[14:15]
	v_pk_mul_f32 v[48:49], v[136:137], v[8:9]
	v_pk_fma_f32 v[48:49], v[128:129], v[0:1], v[48:49]
	v_pk_fma_f32 v[48:49], v[144:145], v[16:17], v[48:49]
	v_pk_add_f32 v[48:49], v[152:153], v[48:49]
	v_pk_mul_f32 v[56:57], v[48:49], v[24:25]
	v_pk_mul_f32 v[50:51], v[138:139], v[10:11]
	v_pk_fma_f32 v[50:51], v[130:131], v[2:3], v[50:51]
	v_pk_fma_f32 v[50:51], v[146:147], v[18:19], v[50:51]
	v_pk_add_f32 v[50:51], v[154:155], v[50:51]
	v_pk_mul_f32 v[58:59], v[50:51], v[26:27]
	v_pk_mul_f32 v[52:53], v[140:141], v[12:13]
	v_pk_fma_f32 v[52:53], v[132:133], v[4:5], v[52:53]
	v_pk_fma_f32 v[52:53], v[148:149], v[20:21], v[52:53]
	v_pk_add_f32 v[52:53], v[156:157], v[52:53]
	v_pk_mul_f32 v[60:61], v[52:53], v[28:29]
	v_pk_mul_f32 v[54:55], v[142:143], v[14:15]
	v_pk_fma_f32 v[54:55], v[134:135], v[6:7], v[54:55]
	v_pk_fma_f32 v[54:55], v[150:151], v[22:23], v[54:55]
	v_pk_add_f32 v[54:55], v[158:159], v[54:55]
	v_pk_mul_f32 v[62:63], v[54:55], v[30:31]
	v_cvt_pk_bf16_f32 v44, v56, v57
	v_cvt_pk_bf16_f32 v45, v58, v59
	v_cvt_pk_bf16_f32 v46, v60, v61
	v_cvt_pk_bf16_f32 v47, v62, v63
	global_store_dwordx4 v[166:167], v[44:47], off
	v_lshl_add_u64 v[166:167], v[166:167], 0, s[14:15]
	s_add_u32 s4, s4, s12
	s_branch .Lcv_loop
